# strategy 2 prologue de-serialisation: A unit prologue issues tile0+tile1 K/V loads together; LUT->LDS copies of A/C/B issue all loads then one wait
# speedup vs baseline: 1.0089x; 1.0065x over previous
; #define FLAS __attribute__((address_space(3)))
; __device__ __forceinline__ void attn_unit_a(FLAS unsigned char* lds, const Unit u) {
;     ...
;     if (u.load_lut) { FLAS float* Lw = (FLAS float*)(lds + LA_LUT); for (int i = tid; i < LUT_N; i += 512) Lw[i] = u.lut[i]; }
.LBB0_416:
	s_mov_b32 s0, s42
	s_bfe_u32 s42, s43, 0x20004
	s_cmp_lg_u32 s42, s0
	v_mov_b32_e32 v4, v236
	s_movk_i32 s4, 0xa80
	s_cselect_b64 s[0:1], -1, 0
	s_nop 0
	v_cmp_gt_i32_e32 vcc, s4, v4
	v_readfirstlane_b32 s18, v4
	s_and_b64 s[4:5], s[0:1], vcc
	s_and_saveexec_b64 s[0:1], s[4:5]
	s_cbranch_execz .LBB0_424
	s_mul_i32 s12, s42, 0x2a00
	s_add_u32 s14, s70, s12
	s_addc_u32 s15, s71, 0
	v_lshlrev_b32_e32 v0, 2, v4
	v_add_u32_e32 v1, 0x1000, v0
	v_add_u32_e32 v2, 0x2000, v0
	v_add_u32_e32 v3, 0x16000, v0
	global_load_dword v5, v0, s[14:15]
	global_load_dword v6, v0, s[14:15] offset:2048
	global_load_dword v7, v1, s[14:15]
	global_load_dword v8, v1, s[14:15] offset:2048
	global_load_dword v9, v2, s[14:15]
	v_cmp_gt_u32_e32 vcc, 0x80, v4
	s_and_saveexec_b64 s[4:5], vcc
	s_cbranch_execz .Llut_a_s1
	global_load_dword v10, v2, s[14:15] offset:2048
.Llut_a_s1:
	s_or_b64 exec, exec, s[4:5]
	s_waitcnt vmcnt(0)
	ds_write_b32 v3, v5
	ds_write_b32 v3, v6 offset:2048
	ds_write_b32 v3, v7 offset:4096
	ds_write_b32 v3, v8 offset:6144
	ds_write_b32 v3, v9 offset:8192
	s_and_saveexec_b64 s[4:5], vcc
	s_cbranch_execz .Llut_a_s2
	ds_write_b32 v3, v10 offset:10240

; #define FLAS __attribute__((address_space(3)))
; __device__ __forceinline__ void attn_unit_a(FLAS unsigned char* lds, const Unit u) {
;     ...
;     { const bf16_t* qp = u.Q + (size_t)(u.tok0 + q) * u.ldq + hi * 8;
; #pragma unroll
;       for (int d0 = 0; d0 < 4; ++d0) qr[d0] = *(const bf16x8*)(qp + d0 * 16); }
;     const bf16_t* ksrc = u.K + (size_t)(u.tok0 + (tid >> 3)) * u.ldk + (tid & 7) * 8;
;     const bf16_t* vsrc = u.VT + (size_t)(tid >> 3) * MTOK + u.tok0 + (tid & 7) * 8;
;     const int kdst = (tid & 7) * 1024 + (((tid >> 3) ^ (tid & 7)) * 16), vdst = (tid >> 3) * VPITCH + ((tid & 7) >> 1) * 32 + (tid & 1) * 8;
;     const int NT = u.t_hi - u.t_lo;
;     u32x4 kreg, vreg[2];
; #pragma unroll
;     for (int j = 0; j < 2; ++j) {
;         kreg = *(const u32x4*)(ksrc + (size_t)(u.t_lo + j) * 64 * u.ldk);
; #pragma unroll
;         for (int i = 0; i < 2; ++i) vreg[i] = *(const u32x4*)(vsrc + (size_t)i * 64 * MTOK + (u.t_lo + j) * 64);
;         *(FLAS u32x4*)(lds + LA_K + j * KBUF + kdst) = kreg;
; #pragma unroll
;         for (int i = 0; i < 2; ++i) { *(FLAS u32x2*)(lds + LA_V + j * VBUF + vdst + i * 64 * VPITCH) = (u32x2){vreg[i].x, vreg[i].y}; *(FLAS u32x2*)(lds + LA_V + j * VBUF + vdst + i * 64 * VPITCH + 16) = (u32x2){vreg[i].z, vreg[i].w}; } }
;     __syncthreads();
;     ...
;     { bool zi; FA_BIAS(0, pa0, pa1, cbC, zi); if (zi) { pa0 = z16; pa1 = z16; }
.LBB0_424:
	s_or_b64 exec, exec, s[0:1]
	s_ashr_i32 s5, s43, 5
	s_and_b32 s0, s43, 15
	s_and_b32 s1, s5, 0xfffff0
	s_bfe_u32 s44, s43, 0x10008
	s_or_b32 s14, s1, s0
	s_lshl_b32 s4, s42, 8
	v_readlane_b32 s0, v252, 4
	v_readlane_b32 s1, v252, 5
	s_add_u32 s45, s0, s4
	s_addc_u32 s46, s1, 0
	s_lshl_b32 s12, s44, 7
	s_add_u32 s0, s45, s12
	s_addc_u32 s1, s46, 0
	s_add_u32 s15, s29, s4
	v_readlane_b32 s19, v252, 7
	s_addc_u32 s19, s19, 0
	s_add_u32 s20, s15, s12
	s_addc_u32 s21, s19, 0
	s_lshl_b32 s12, s42, 23
	s_add_u32 s22, s30, s12
	s_addc_u32 s23, s31, 0
	s_lshl_b32 s19, s14, 8
	s_ashr_i32 s14, s18, 1
	s_andn2_b32 s14, s14, 31
	s_lshl_b32 s15, s43, 7
	v_and_b32_e32 v5, 31, v4
	s_add_i32 s47, s14, s19
	s_and_b32 s15, s15, 0x6000
	v_or_b32_e32 v244, s47, v5
	v_bfe_u32 v243, v4, 5, 1
	v_add_u32_e32 v222, s15, v244
	v_mov_b64_e32 v[0:1], s[0:1]
	v_mad_i64_i32 v[0:1], s[0:1], v222, s65, v[0:1]
	v_lshlrev_b32_e32 v224, 4, v243
	v_mov_b32_e32 v225, v209
	v_lshl_add_u64 v[0:1], v[0:1], 0, v[224:225]
	global_load_dwordx4 v[160:163], v[0:1], off
	global_load_dwordx4 v[164:167], v[0:1], off offset:32
	global_load_dwordx4 v[168:171], v[0:1], off offset:64
	global_load_dwordx4 v[172:175], v[0:1], off offset:96
	v_ashrrev_i32_e32 v0, 3, v4
	v_add_u32_e32 v1, s15, v0
	v_mov_b64_e32 v[2:3], s[20:21]
	v_and_b32_e32 v8, 7, v4
	v_mad_i64_i32 v[2:3], s[0:1], v1, s65, v[2:3]
	v_lshlrev_b32_e32 v208, 4, v8
	v_ashrrev_i32_e32 v1, 31, v0
	v_lshl_add_u64 v[18:19], v[2:3], 0, v[208:209]
	v_lshlrev_b64 v[2:3], 16, v[0:1]
	v_lshl_add_u64 v[6:7], s[22:23], 0, v[2:3]
	s_lshl_b32 s26, s15, 1
	v_lshl_add_u64 v[6:7], v[6:7], 0, s[26:27]
	v_lshl_add_u64 v[20:21], v[6:7], 0, v[208:209]
	v_lshlrev_b32_e32 v1, 10, v8
	v_bitop3_b32 v6, v0, v4, 7 bitop3:0x78
	v_lshl_add_u32 v1, v6, 4, v1
	v_lshlrev_b32_e32 v6, 4, v4
	v_and_b32_e32 v6, 0x60, v6
	s_movk_i32 s0, 0x90
	v_mad_u64_u32 v[6:7], s[0:1], v0, s0, v[6:7]
	s_mov_b32 s0, 0x400000
	v_lshlrev_b32_e32 v4, 3, v4
	v_add_co_u32_e32 v22, vcc, s0, v20
	v_and_or_b32 v4, v4, 8, v6
	global_load_dwordx4 v[6:9], v[18:19], off
	global_load_dwordx4 v[10:13], v[20:21], off
	v_addc_co_u32_e32 v23, vcc, 0, v21, vcc
	global_load_dwordx4 v[14:17], v[22:23], off
	v_add_co_u32_e32 v28, vcc, 0x30000, v18
	s_nop 1
	v_addc_co_u32_e32 v29, vcc, 0, v19, vcc
	global_load_dwordx4 v[176:179], v[28:29], off
	global_load_dwordx4 v[180:183], v[20:21], off offset:128
	global_load_dwordx4 v[184:187], v[22:23], off offset:128
	v_add_u32_e32 v245, 0, v4
	v_add_u32_e32 v225, 0, v1
	v_add_u32_e32 v1, 0x4000, v245
	s_mov_b32 s0, 0x30000
	s_cmpk_gt_i32 s47, 0xfdb2
	s_waitcnt vmcnt(5)
	ds_write_b128 v225, v[6:9]
	s_waitcnt vmcnt(4)
	ds_write2_b64 v1, v[10:11], v[12:13] offset1:2
	v_add_u32_e32 v1, 0x6000, v245
	s_waitcnt vmcnt(3)
	ds_write2_b64 v1, v[14:15], v[16:17] offset0:128 offset1:130
	v_add_u32_e32 v1, 0x8800, v245
	s_mov_b64 s[0:1], -1
	s_waitcnt vmcnt(2)
	ds_write_b128 v225, v[176:179] offset:8192
	s_waitcnt vmcnt(1)
	ds_write2_b64 v1, v[180:181], v[182:183] offset1:2
	v_add_u32_e32 v1, 0xa800, v245
	s_waitcnt vmcnt(0)
	ds_write2_b64 v1, v[184:185], v[186:187] offset0:128 offset1:130
	s_waitcnt lgkmcnt(0)
	s_barrier
	s_cbranch_scc0 .LBB0_430
	s_cmpk_lt_i32 s47, 0x26e
	s_cbranch_scc0 .LBB0_427
	v_lshlrev_b32_e32 v1, 2, v244
	v_sub_u32_e32 v1, 0, v1
	s_mov_b32 s0, 0x16000
	v_add3_u32 v1, v1, v224, s0
	v_add_u32_e32 v4, 0x1500, v1
	v_add_u32_e32 v6, 0x1580, v1
	v_add_u32_e32 v7, 0x1508, v1
	v_add_u32_e32 v8, 0x1588, v1
	ds_read2_b32 v[128:129], v4 offset1:1
	ds_read2_b32 v[144:145], v6 offset1:1
	ds_read2_b32 v[130:131], v7 offset1:1
	ds_read2_b32 v[146:147], v8 offset1:1
	v_add_u32_e32 v4, 0x1520, v1
	v_add_u32_e32 v6, 0x15a0, v1
	v_add_u32_e32 v7, 0x1528, v1
	v_add_u32_e32 v8, 0x15a8, v1
	ds_read2_b32 v[132:133], v4 offset1:1
	ds_read2_b32 v[148:149], v6 offset1:1
	ds_read2_b32 v[134:135], v7 offset1:1
	ds_read2_b32 v[150:151], v8 offset1:1
	v_add_u32_e32 v4, 0x1540, v1
	v_add_u32_e32 v6, 0x15c0, v1
	v_add_u32_e32 v7, 0x1548, v1
	v_add_u32_e32 v8, 0x15c8, v1
	ds_read2_b32 v[136:137], v4 offset1:1
	ds_read2_b32 v[152:153], v6 offset1:1
	ds_read2_b32 v[138:139], v7 offset1:1
	ds_read2_b32 v[154:155], v8 offset1:1
	v_add_u32_e32 v4, 0x1560, v1
	v_add_u32_e32 v6, 0x15e0, v1
	v_add_u32_e32 v7, 0x1568, v1
	v_add_u32_e32 v1, 0x15e8, v1
	ds_read2_b32 v[140:141], v4 offset1:1
	ds_read2_b32 v[156:157], v6 offset1:1
	ds_read2_b32 v[142:143], v7 offset1:1
	ds_read2_b32 v[158:159], v1 offset1:1
	s_mov_b64 s[0:1], 0

; #define FLAS __attribute__((address_space(3)))
; template <int MODE> __device__ __forceinline__ void attn_unit(FLAS unsigned char* lds, const Unit u) {
;     ...
;     if (u.load_lut) { FLAS float* L = (FLAS float*)(lds + L_LUT); const int n = (MODE == 1) ? 15 * 128 : LUT_N; for (int i = tid; i < n; i += 512) L[i] = u.lut[i]; }
;     ...
;     { const bf16_t* qp = u.Q + (size_t)(u.tok0 + q) * u.ldq + hi * 8;
; #pragma unroll
;       for (int d0 = 0; d0 < 4; ++d0) qr[d0] = *(const bf16x8*)(qp + d0 * 16); }
;     const bf16_t* ksrc = u.K + (size_t)(u.tok0 + (tid >> 3)) * u.ldk + (tid & 7) * 8;
;     const bf16_t* vsrc = u.VT + (size_t)(tid >> 3) * MTOK + u.tok0 + (tid & 7) * 8;
;     const int kdst = (tid & 7) * 1024 + (((tid >> 3) ^ (tid & 7)) * 16), vdst = (tid >> 3) * VPITCH + ((tid & 7) >> 1) * 32 + (tid & 1) * 8;
;     u32x4 kreg, vreg[NVR];
;     kreg = *(const u32x4*)(ksrc + (size_t)u.t_lo * 64 * u.ldk);
; #pragma unroll
;     for (int i = 0; i < NVR; ++i) vreg[i] = *(const u32x4*)(vsrc + (size_t)i * 64 * MTOK + u.t_lo * 64);
;     *(FLAS u32x4*)(lds + L_K + kdst) = kreg;
; #pragma unroll
;     for (int i = 0; i < NVR; ++i) { *(FLAS u32x2*)(lds + L_V + vdst + i * 64 * VPITCH) = (u32x2){vreg[i].x, vreg[i].y}; *(FLAS u32x2*)(lds + L_V + vdst + i * 64 * VPITCH + 16) = (u32x2){vreg[i].z, vreg[i].w}; }
;     __syncthreads();
.LBB0_486:
	s_mov_b32 s0, s18
	s_bfe_u32 s18, s19, 0x30003
	s_cmp_lg_u32 s18, s0
	v_mov_b32_e32 v2, v236
	s_movk_i32 s4, 0xa80
	s_cselect_b64 s[0:1], -1, 0
	s_nop 0
	v_cmp_gt_i32_e32 vcc, s4, v2
	v_readfirstlane_b32 s12, v2
	s_and_b64 s[4:5], s[0:1], vcc
	s_and_saveexec_b64 s[0:1], s[4:5]
	s_cbranch_execz .LBB0_494
	s_mul_i32 s20, s18, 0x2a00
	v_readlane_b32 s6, v253, 59
	v_readlane_b32 s7, v253, 60
	s_nop 3
	s_add_u32 s6, s6, s20
	s_addc_u32 s7, s7, 0
	v_readlane_b32 s8, v254, 49
	v_lshlrev_b32_e32 v0, 2, v2
	v_add_u32_e32 v1, 0x1000, v0
	v_add_u32_e32 v3, 0x2000, v0
	v_add_u32_e32 v4, s8, v0
	global_load_dword v5, v0, s[6:7]
	global_load_dword v6, v0, s[6:7] offset:2048
	global_load_dword v7, v1, s[6:7]
	global_load_dword v8, v1, s[6:7] offset:2048
	global_load_dword v9, v3, s[6:7]
	v_cmp_gt_u32_e32 vcc, 0x80, v2
	s_and_saveexec_b64 s[4:5], vcc
	s_cbranch_execz .Llut_c_s1
	global_load_dword v10, v3, s[6:7] offset:2048
.Llut_c_s1:
	s_or_b64 exec, exec, s[4:5]
	s_waitcnt vmcnt(0)
	ds_write_b32 v4, v5
	ds_write_b32 v4, v6 offset:2048
	ds_write_b32 v4, v7 offset:4096
	ds_write_b32 v4, v8 offset:6144
	ds_write_b32 v4, v9 offset:8192
	s_and_saveexec_b64 s[4:5], vcc
	s_cbranch_execz .Llut_c_s2
	ds_write_b32 v4, v10 offset:10240
.Llut_c_s2:
	s_or_b64 exec, exec, s[4:5]
.LBB0_494:
	s_or_b64 exec, exec, s[0:1]
	s_ashr_i32 s1, s19, 5
	s_and_b32 s0, s19, 7
	s_and_b32 s4, s1, -8
	s_or_b32 s4, s4, s0
	s_lshl_b32 s0, s18, 7
	v_readlane_b32 s5, v253, 55
	s_add_u32 s6, s5, s0
	v_readlane_b32 s5, v253, 56
	s_addc_u32 s7, s5, 0
	v_readlane_b32 s5, v253, 57
	s_add_u32 s22, s5, s0
	v_readlane_b32 s5, v253, 58
	s_addc_u32 s23, s5, 0
	s_lshl_b32 s5, s18, 22
	s_add_u32 s24, s30, s5
	s_addc_u32 s25, s31, 0
	s_lshl_b32 s9, s4, 8
	s_lshl_b32 s4, s4, 2
	s_max_i32 s8, s4, 16
	s_min_i32 s20, s4, 0x6c
	s_ashr_i32 s4, s12, 1
	s_and_b32 s21, s4, 0xffffffe0
	s_lshl_b32 s5, s19, 7
	v_and_b32_e32 v3, 31, v2
	s_add_i32 s21, s21, s9
	s_and_b32 s5, s5, 0x6000
	v_or_b32_e32 v0, s21, v3
	v_bfe_u32 v134, v2, 5, 1
	v_add_u32_e32 v4, s5, v0
	v_mov_b64_e32 v[0:1], s[6:7]
	v_mad_i64_i32 v[96:97], s[6:7], v4, s65, v[0:1]
	v_lshlrev_b32_e32 v208, 4, v134
	v_lshl_add_u64 v[0:1], v[96:97], 0, v[208:209]
	global_load_dwordx4 v[64:67], v[0:1], off
	global_load_dwordx4 v[68:71], v[0:1], off offset:32
	global_load_dwordx4 v[72:75], v[0:1], off offset:64
	global_load_dwordx4 v[76:79], v[0:1], off offset:96
	v_ashrrev_i32_e32 v0, 3, v2
	v_add_u32_e32 v1, s5, v0
	v_mov_b64_e32 v[4:5], s[22:23]
	v_mad_i64_i32 v[6:7], s[6:7], v1, s65, v[4:5]
	v_ashrrev_i32_e32 v1, 31, v0
	v_lshlrev_b64 v[8:9], 16, v[0:1]
	v_and_b32_e32 v10, 7, v2
	v_lshl_add_u64 v[8:9], s[24:25], 0, v[8:9]
	s_lshl_b32 s26, s5, 1
	v_lshlrev_b32_e32 v4, 4, v10
	v_mov_b32_e32 v5, v209
	v_lshl_add_u64 v[8:9], v[8:9], 0, s[26:27]
	s_add_i32 s8, s8, -16
	v_lshl_add_u64 v[6:7], v[6:7], 0, v[4:5]
	v_lshl_add_u64 v[8:9], v[8:9], 0, v[4:5]
	s_mov_b64 s[6:7], 0x4000000
	v_lshl_add_u64 v[98:99], v[8:9], 0, s[6:7]
	v_mad_u64_u32 v[6:7], s[6:7], s8, v241, v[6:7]
	s_lshl_b32 s26, s8, 6
	global_load_dwordx4 v[80:83], v[6:7], off
	v_lshl_add_u64 v[6:7], s[26:27], 1, v[98:99]
	global_load_dwordx4 v[84:87], v[6:7], off
	v_bitop3_b32 v5, v0, v2, 7 bitop3:0x78
	v_lshlrev_b32_e32 v9, 4, v2
	v_lshlrev_b32_e32 v1, 10, v10
	v_lshlrev_b32_e32 v5, 4, v5
	s_movk_i32 s5, 0x90
	v_and_b32_e32 v9, 0x60, v9
	v_lshlrev_b32_e32 v2, 3, v2
	v_mul_lo_u32 v8, v0, s5
	v_and_b32_e32 v2, 8, v2
	v_add3_u32 v135, 0, v5, v1
	v_add_u32_e32 v1, 0, v9
	s_add_i32 s20, s20, 20
	v_add3_u32 v136, v1, v8, v2
	v_add_u32_e32 v1, 0x4000, v136
	s_cmp_ge_i32 s8, s20
	s_waitcnt vmcnt(1)
	ds_write_b128 v135, v[80:83]
	s_waitcnt vmcnt(0)
	ds_write2_b64 v1, v[84:85], v[86:87] offset1:2
	s_waitcnt lgkmcnt(0)
	s_barrier
	s_cbranch_scc1 .LBB0_484
	v_mul_u32_u24_e32 v1, 0x90, v3
	v_add3_u32 v138, 0, v1, v208
	v_xor_b32_e32 v1, v134, v3
	v_lshlrev_b32_e32 v140, 4, v1
	v_or_b32_e32 v1, 2, v134
	v_lshlrev_b32_e32 v141, 10, v1
	v_bitop3_b32 v1, v134, v3, 2 bitop3:0x36
	s_and_b32 s5, s15, 7
	v_lshlrev_b32_e32 v142, 4, v1
	v_or_b32_e32 v1, 4, v134
	s_lshr_b32 s1, s1, 3
	s_lshl_b32 s6, s5, 2
	v_lshlrev_b32_e32 v143, 10, v1
	v_bitop3_b32 v1, v134, v3, 4 bitop3:0x36
	s_lshl_b32 s9, s1, 5
	v_lshlrev_b32_e32 v144, 4, v1
	v_or_b32_e32 v1, 6, v134
	s_or_b32 s6, s9, s6
	v_lshlrev_b32_e32 v145, 10, v1
	v_bitop3_b32 v1, v134, v3, 6 bitop3:0x36
	s_max_i32 s6, s6, 16
	v_lshlrev_b32_e32 v146, 4, v1
	v_lshl_or_b32 v1, s6, 8, v208
	v_lshlrev_b32_e32 v2, 2, v3
	s_lshl_b32 s4, s4, 2
	v_sub_u32_e32 v1, v1, v2
	s_and_b32 s4, s4, 0xffffff80
	s_lshl_b32 s5, s5, 10
	v_subrev_u32_e32 v1, s4, v1
	v_subrev_u32_e32 v1, s5, v1
	s_lshl_b32 s1, s1, 13
	v_subrev_u32_e32 v1, s1, v1
	v_readlane_b32 s1, v254, 50
	s_bfe_u32 s7, s14, 0x2000d
	s_mul_i32 s7, s7, 0x1800000
	v_add_u32_e32 v147, s1, v1
	s_lshl_b32 s1, s6, 6
	s_add_i32 s22, s1, 0xfffffc00
	s_add_i32 s1, s6, -16
	s_add_i32 s12, s21, 0xfffffc00
	s_addk_i32 s21, 0x41f
	s_mul_hi_u32 s5, s1, 0x30000
	s_mul_i32 s1, s1, 0x30000
	s_add_u32 s4, s7, s1
	s_addc_u32 s5, 0, s5
	v_mov_b64_e32 v[2:3], s[4:5]
	v_mad_i64_i32 v[0:1], s[4:5], v0, s65, v[2:3]
	v_or3_b32 v0, v0, s0, v4
	v_readlane_b32 s0, v254, 40
	v_readlane_b32 s1, v254, 41
	v_mov_b32_e32 v148, 0
	v_lshlrev_b32_e32 v139, 10, v134
	v_lshl_add_u64 v[100:101], s[0:1], 0, v[0:1]
	s_mov_b64 s[6:7], -1
	v_mov_b32_e32 v137, 0
	v_mov_b32_e32 v0, 0
	v_mov_b32_e32 v1, v148
	v_mov_b32_e32 v2, v148
	v_mov_b32_e32 v3, v148
	v_mov_b32_e32 v4, v148
	v_mov_b32_e32 v5, v148
	v_mov_b32_e32 v6, v148
	v_mov_b32_e32 v7, v148
	v_mov_b32_e32 v8, v148
	v_mov_b32_e32 v9, v148
	v_mov_b32_e32 v10, v148
	v_mov_b32_e32 v11, v148
	v_mov_b32_e32 v12, v148
	v_mov_b32_e32 v13, v148
	v_mov_b32_e32 v14, v148
	v_mov_b32_e32 v15, v148
	v_mov_b32_e32 v16, v148
	v_mov_b32_e32 v17, v148
	v_mov_b32_e32 v18, v148
	v_mov_b32_e32 v19, v148
	v_mov_b32_e32 v20, v148
	v_mov_b32_e32 v21, v148
	v_mov_b32_e32 v22, v148
	v_mov_b32_e32 v23, v148
	v_mov_b32_e32 v24, v148
	v_mov_b32_e32 v25, v148
	v_mov_b32_e32 v26, v148
	v_mov_b32_e32 v27, v148
	v_mov_b32_e32 v28, v148
	v_mov_b32_e32 v29, v148
	v_mov_b32_e32 v30, v148
	v_mov_b32_e32 v31, v148

; #define FLAS __attribute__((address_space(3)))
; template <int MODE> __device__ __forceinline__ void attn_unit(FLAS unsigned char* lds, const Unit u) {
;     ...
;     if (u.load_lut) { FLAS float* L = (FLAS float*)(lds + L_LUT); const int n = (MODE == 1) ? 15 * 128 : LUT_N; for (int i = tid; i < n; i += 512) L[i] = u.lut[i]; }
;     ...
;     { const bf16_t* qp = u.Q + (size_t)(u.tok0 + q) * u.ldq + hi * 8;
; #pragma unroll
;       for (int d0 = 0; d0 < 4; ++d0) qr[d0] = *(const bf16x8*)(qp + d0 * 16); }
;     const bf16_t* ksrc = u.K + (size_t)(u.tok0 + (tid >> 3)) * u.ldk + (tid & 7) * 8;
;     const bf16_t* vsrc = u.VT + (size_t)(tid >> 3) * MTOK + u.tok0 + (tid & 7) * 8;
;     const int kdst = (tid & 7) * 1024 + (((tid >> 3) ^ (tid & 7)) * 16), vdst = (tid >> 3) * VPITCH + ((tid & 7) >> 1) * 32 + (tid & 1) * 8;
;     u32x4 kreg, vreg[NVR];
;     kreg = *(const u32x4*)(ksrc + (size_t)u.t_lo * 64 * u.ldk);
; #pragma unroll
;     for (int i = 0; i < NVR; ++i) vreg[i] = *(const u32x4*)(vsrc + (size_t)i * 64 * MTOK + u.t_lo * 64);
;     *(FLAS u32x4*)(lds + L_K + kdst) = kreg;
; #pragma unroll
;     for (int i = 0; i < NVR; ++i) { *(FLAS u32x2*)(lds + L_V + vdst + i * 64 * VPITCH) = (u32x2){vreg[i].x, vreg[i].y}; *(FLAS u32x2*)(lds + L_V + vdst + i * 64 * VPITCH + 16) = (u32x2){vreg[i].z, vreg[i].w}; }
;     __syncthreads();
.LBB0_516:
	s_mov_b32 s0, s34
	s_lshr_b32 s12, s19, 3
	s_bfe_u32 s34, s19, 0x30003
	s_cmp_lg_u32 s34, s0
	v_mov_b32_e32 v4, v236
	s_movk_i32 s4, 0x780
	s_cselect_b64 s[0:1], -1, 0
	s_nop 0
	v_cmp_gt_i32_e32 vcc, s4, v4
	v_readfirstlane_b32 s15, v4
	s_and_b64 s[4:5], s[0:1], vcc
	s_and_saveexec_b64 s[0:1], s[4:5]
	s_cbranch_execz .LBB0_524
	s_and_b32 s4, s12, 7
	v_readlane_b32 s6, v254, 52
	s_mulk_i32 s4, 0x780
	s_nop 3
	s_mul_i32 s5, s6, 0x3c00
	s_add_i32 s26, s5, s4
	s_lshl_b64 s[4:5], s[26:27], 2
	v_readlane_b32 s6, v254, 1
	v_readlane_b32 s7, v254, 2
	s_nop 3
	s_add_u32 s6, s6, s4
	s_addc_u32 s7, s7, s5
	v_readlane_b32 s8, v254, 49
	v_lshlrev_b32_e32 v0, 2, v4
	v_add_u32_e32 v1, 0x1000, v0
	v_add_u32_e32 v3, s8, v0
	global_load_dword v5, v0, s[6:7]
	global_load_dword v6, v0, s[6:7] offset:2048
	global_load_dword v7, v1, s[6:7]
	v_cmp_gt_u32_e32 vcc, 0x180, v4
	s_and_saveexec_b64 s[4:5], vcc
	s_cbranch_execz .Llut_b_s1
	global_load_dword v8, v1, s[6:7] offset:2048
.Llut_b_s1:
	s_or_b64 exec, exec, s[4:5]
	s_waitcnt vmcnt(0)
	ds_write_b32 v3, v5
	ds_write_b32 v3, v6 offset:2048
	ds_write_b32 v3, v7 offset:4096
	s_and_saveexec_b64 s[4:5], vcc
	s_cbranch_execz .Llut_b_s2
	ds_write_b32 v3, v8 offset:6144
.Llut_b_s2:
	s_or_b64 exec, exec, s[4:5]
.LBB0_524:
	s_or_b64 exec, exec, s[0:1]
	s_ashr_i32 s20, s19, 5
	s_and_b32 s0, s19, 7
	s_and_b32 s1, s20, -8
	s_or_b32 s7, s1, s0
	s_lshl_b32 s4, s34, 7
	v_readlane_b32 s0, v253, 61
	s_add_u32 s0, s0, s4
	v_readlane_b32 s1, v253, 62
	s_addc_u32 s1, s1, 0
	v_readlane_b32 s5, v253, 63
	s_add_u32 s4, s5, s4
	v_readlane_b32 s5, v254, 0
	s_addc_u32 s5, s5, 0
	s_lshl_b32 s6, s34, 22
	s_add_u32 s8, s30, s6
	s_addc_u32 s9, s31, 0
	s_lshl_b32 s6, s19, 7
	s_and_b32 s21, s6, 0x6000
	s_lshl_b32 s6, s7, 2
	s_min_i32 s23, s6, 0x79
	s_lshl_b32 s22, s7, 8
	s_add_i32 s14, s6, -4
	s_add_i32 s23, s23, 7
	s_cmp_lt_i32 s7, 1
	s_cselect_b32 s14, 0, s14
	s_cselect_b32 s35, 8, s23
	v_and_b32_e32 v5, 31, v4
	s_ashr_i32 s7, s15, 1
	s_add_i32 s22, s22, s21
	s_and_b32 s23, s7, 0xffffffe0
	v_or_b32_e32 v0, s22, v5
	v_bfe_u32 v6, v4, 5, 1
	v_add_u32_e32 v2, s23, v0
	v_mov_b64_e32 v[0:1], s[0:1]
	v_mad_i64_i32 v[96:97], s[0:1], v2, s65, v[0:1]
	v_lshlrev_b32_e32 v208, 4, v6
	v_lshl_add_u64 v[0:1], v[96:97], 0, v[208:209]
	global_load_dwordx4 v[64:67], v[0:1], off
	global_load_dwordx4 v[68:71], v[0:1], off offset:32
	global_load_dwordx4 v[72:75], v[0:1], off offset:64
	global_load_dwordx4 v[76:79], v[0:1], off offset:96
	v_ashrrev_i32_e32 v0, 3, v4
	v_add_u32_e32 v1, s21, v0
	v_mov_b64_e32 v[2:3], s[4:5]
	v_mad_i64_i32 v[8:9], s[0:1], v1, s65, v[2:3]
	v_ashrrev_i32_e32 v1, 31, v0
	v_lshlrev_b64 v[10:11], 16, v[0:1]
	v_and_b32_e32 v7, 7, v4
	v_lshl_add_u64 v[10:11], s[8:9], 0, v[10:11]
	s_lshl_b32 s26, s21, 1
	v_lshlrev_b32_e32 v2, 4, v7
	v_mov_b32_e32 v3, v209
	v_lshl_add_u64 v[10:11], v[10:11], 0, s[26:27]
	v_lshl_add_u64 v[10:11], v[10:11], 0, v[2:3]
	s_mov_b64 s[0:1], 0x2000000
	v_lshl_add_u64 v[8:9], v[8:9], 0, v[2:3]
	v_lshl_add_u64 v[98:99], v[10:11], 0, s[0:1]
	s_movk_i32 s0, 0x90
	v_lshlrev_b32_e32 v1, 10, v7
	v_mul_lo_u32 v7, v0, s0
	v_mad_i64_i32 v[8:9], s[0:1], s14, v241, v[8:9]
	s_lshl_b32 s0, s14, 6
	s_ashr_i32 s1, s0, 31
	global_load_dwordx4 v[80:83], v[8:9], off
	v_lshl_add_u64 v[8:9], s[0:1], 1, v[98:99]
	global_load_dwordx4 v[84:87], v[8:9], off
	v_bitop3_b32 v3, v0, v4, 7 bitop3:0x78
	v_lshlrev_b32_e32 v10, 4, v4
	v_lshlrev_b32_e32 v3, 4, v3
	v_and_b32_e32 v10, 0x60, v10
	v_lshlrev_b32_e32 v4, 3, v4
	v_and_b32_e32 v4, 8, v4
	v_add3_u32 v134, 0, v3, v1
	v_add_u32_e32 v1, 0, v10
	v_add3_u32 v135, v1, v7, v4
	v_add_u32_e32 v1, 0x4000, v135
	s_mov_b64 s[4:5], -1
	s_cmp_lt_i32 s14, s35
	v_lshlrev_b32_e32 v136, 2, v6
	s_waitcnt vmcnt(1)
	ds_write_b128 v134, v[80:83]
	s_waitcnt vmcnt(0)
	ds_write2_b64 v1, v[84:85], v[86:87] offset1:2
	s_waitcnt lgkmcnt(0)
	s_barrier
	s_cbranch_scc1 .LBB0_526
	v_lshlrev_b32_e32 v32, 2, v6
	s_mov_b64 s[4:5], 0
